# grid barrier: XCD leaders no longer wait for the acknowledgements of their release atomics before entering the next phase
# baseline (speedup 1.0000x reference)
; #define LAS __attribute__((address_space(3)))
; __global__ void __launch_bounds__(256, 2) mega(P p, int ph_lo, int ph_hi, int coop) {
;     ...
;   if (coop) {
;     if (__builtin_amdgcn_workitem_id_x() == 0) xb_words = make_uint4(0u, 0u, 0u, 0u);
;     __syncthreads();
;     xb = xcd_barrier_post((unsigned*)(p.ws + W_BAR), (volatile LAS unsigned*)&xb_words);
;   }
.LBB0_10:
	s_or_b64 exec, exec, s[6:7]
.LBB0_11:
	s_or_b64 exec, exec, s[2:3]
	s_waitcnt lgkmcnt(0)
	s_barrier

; DI unsigned xb_ld(unsigned* p) { return __hip_atomic_load(p, __ATOMIC_RELAXED, __HIP_MEMORY_SCOPE_AGENT); }
; DI unsigned xb_add(unsigned* p, unsigned v) { return __hip_atomic_fetch_add(p, v, __ATOMIC_RELAXED, __HIP_MEMORY_SCOPE_AGENT); }
; #define XB_SPIN(cond, bar) do { unsigned _sp = 0; while (cond) { __builtin_amdgcn_s_sleep(1); \
;     if ((++_sp & 255u) == 0u) { if (xb_ld(&(bar)[XB_TMO])) break; if (_sp > XB_SPIN_CAP) { atomicAdd(&(bar)[XB_TMO], 1u); break; } } } } while (0)
; DI void xcd_barrier(const XcdBarrier& b) {
;     ...
;       if (og + 1u == (tg + 1u) * nx) xb_add(&bar[XB_TOPGEN], 1u);
;       else XB_SPIN(xb_ld(&bar[XB_TOPGEN]) == tg, bar);
;       __builtin_amdgcn_fence(__ATOMIC_ACQUIRE, "agent");
;       xb_add(&bar[XB_XGEN(b.x)], 1u);
;       asm volatile("s_waitcnt vmcnt(0)" ::: "memory");
.LBB0_2121:
	s_or_b64 exec, exec, s[4:5]
	s_mov_b64 s[4:5], exec
	v_mbcnt_lo_u32_b32 v0, s4, 0
	v_mbcnt_hi_u32_b32 v0, s5, v0
	v_cmp_eq_u32_e32 vcc, 0, v0
	s_and_saveexec_b64 s[6:7], vcc
	s_cbranch_execnz .LBB0_2122
	s_getpc_b64 s[98:99]
